# baseline (speedup 1.0000x reference)
; __device__ __forceinline__ bf16x8 hy_afrag(const bf16_t* gbase, const bool t2, const bool t1, const unsigned sh) {
;   const uint4 lo = *(const uint4*)gbase, hi = *(const uint4*)(gbase + 8);
;   const unsigned x0 = t2 ? lo.z : lo.x, x1 = t2 ? lo.w : lo.y, x2 = t2 ? hi.x : lo.z, x3 = t2 ? hi.y : lo.w,
;                  x4 = t2 ? hi.z : hi.x, x5 = t2 ? hi.w : hi.y;
;   const unsigned y0 = t1 ? x1 : x0, y1 = t1 ? x2 : x1, y2 = t1 ? x3 : x2, y3 = t1 ? x4 : x3, y4 = t1 ? x5 : x4;
;   union { unsigned u[4]; bf16x8 v; } o;
;   o.u[0] = __builtin_amdgcn_alignbit(y1, y0, sh);
;   o.u[1] = __builtin_amdgcn_alignbit(y2, y1, sh);
;   o.u[2] = __builtin_amdgcn_alignbit(y3, y2, sh);
;   o.u[3] = __builtin_amdgcn_alignbit(y4, y3, sh);
;   return o.v;
; }
; template <int LSEL>
; __device__ __forceinline__ void hy_conv(const bf16_t* Z, const bf16_t* G, f32x4 (&acc)[4][4], int w, int lane) {
;     ...
;   for (int d = i_lo - (NB - 1); d <= i_hi; ++d) {
;     bf16x8 bf[4][2];
; #pragma unroll
;     for (int k = 0; k < 4; ++k) {
;       int js = (q0 + k) * BPT - d;
;       js = min(max(js, LSEL ? -1 : 0), NB - 1);
;       const bf16_t* bp = Z + zb + 64 * js;
;       bf[k][0] = *(const bf16x8*)bp;
;       bf[k][1] = *(const bf16x8*)(bp + 32);
;     }
;     const bf16_t* gb = G + (L - 64 * d + 8 * quad - r - s);
;     bf16x8 F[6];
; #pragma unroll
;     for (int u = 0; u < 6; ++u) F[u] = hy_afrag(gb + 16 * (u - 3), t2, t1, sh);
; #pragma unroll
;     for (int k = 0; k < 4; ++k) {
;       const int js = (q0 + k) * BPT - d;
;       const bool valid = LSEL ? (js >= -1 && js <= NB - 1) : (js >= 0 && js <= NB - 1);
;       if (valid) {
; #pragma unroll
;         for (int mt = 0; mt < 4; ++mt) {
;           acc[k][mt] = __builtin_amdgcn_mfma_f32_16x16x32_bf16(F[3 - mt], bf[k][0], acc[k][mt], 0, 0, 0);
;           acc[k][mt] = __builtin_amdgcn_mfma_f32_16x16x32_bf16(F[5 - mt], bf[k][1], acc[k][mt], 0, 0, 0);
;         }
;       }
;     }
;   }
.LBB0_835:
	v_add_u32_e32 v0, s9, v176
	v_mov_b32_e32 v140, v108
	v_mov_b32_e32 v141, v109
	v_mov_b32_e32 v142, v110
	v_mov_b32_e32 v143, v111
	v_mov_b32_e32 v144, v120
	v_mov_b32_e32 v145, v121
	v_mov_b32_e32 v146, v122
	v_mov_b32_e32 v147, v123
	ds_read2_b32 v[108:109], v0 offset1:1
	ds_read2_b32 v[110:111], v0 offset0:2 offset1:3
	ds_read_b32 v2, v0 offset:16
	ds_read2_b32 v[120:121], v0 offset0:8 offset1:9
	ds_read2_b32 v[122:123], v0 offset0:10 offset1:11
	ds_read_b32 v3, v0 offset:48
	ds_read2_b32 v[124:125], v0 offset0:16 offset1:17
	ds_read2_b32 v[126:127], v0 offset0:18 offset1:19
	ds_read_b32 v177, v0 offset:80
	ds_read2_b32 v[136:137], v0 offset0:24 offset1:25
	ds_read2_b32 v[138:139], v0 offset0:26 offset1:27
	ds_read_b32 v178, v0 offset:112
	s_add_i32 s12, s8, 1
	v_med3_i32 v0, s12, 0, 31
	v_lshl_add_u32 v0, v0, 7, v153
	s_add_i32 s11, s8, 2
	ds_read_b128 v[128:131], v0
	ds_read_b128 v[132:135], v0 offset:64
	s_waitcnt lgkmcnt(11)
	v_alignbit_b32 v108, v109, v108, v152
	v_alignbit_b32 v109, v110, v109, v152
	v_alignbit_b32 v110, v111, v110, v152
	v_alignbit_b32 v111, v2, v111, v152
	v_med3_i32 v0, s11, 0, 31
	s_add_i32 s10, s8, 3
	v_lshl_add_u32 v0, v0, 7, v153
	s_min_u32 s13, s10, 31
	ds_read_b128 v[112:115], v0
	ds_read_b128 v[116:119], v0 offset:64
	s_waitcnt lgkmcnt(10)
	v_alignbit_b32 v120, v121, v120, v152
	v_alignbit_b32 v121, v122, v121, v152
	v_alignbit_b32 v122, v123, v122, v152
	v_alignbit_b32 v123, v3, v123, v152
	v_lshl_add_u32 v0, s13, 7, v153
	ds_read_b128 v[100:103], v0
	ds_read_b128 v[104:107], v0 offset:64
	s_waitcnt lgkmcnt(9)
	v_alignbit_b32 v124, v125, v124, v152
	v_alignbit_b32 v125, v126, v125, v152
	v_alignbit_b32 v126, v127, v126, v152
	v_alignbit_b32 v127, v177, v127, v152
	s_waitcnt lgkmcnt(6)
	v_alignbit_b32 v136, v137, v136, v152
	v_alignbit_b32 v137, v138, v137, v152
	v_alignbit_b32 v138, v139, v138, v152
	v_alignbit_b32 v139, v178, v139, v152
	s_waitcnt lgkmcnt(0)
	s_cmp_lt_u32 s8, 29
	s_cbranch_scc0 .Lhy_slow_835
	v_add_u32_e32 v0, s9, v154
	ds_read_b128 v[166:169], v0
	ds_read_b128 v[170:173], v0 offset:64
	s_setprio 1
	v_mfma_f32_16x16x32_bf16 v[64:67], v[136:139], v[112:115], v[64:67]
	v_mfma_f32_16x16x32_bf16 v[60:63], v[124:127], v[112:115], v[60:63]
	v_mfma_f32_16x16x32_bf16 v[56:59], v[120:123], v[112:115], v[56:59]
	v_mfma_f32_16x16x32_bf16 v[52:55], v[108:111], v[112:115], v[52:55]
	v_mfma_f32_16x16x32_bf16 v[64:67], v[144:147], v[116:119], v[64:67]
	v_mfma_f32_16x16x32_bf16 v[60:63], v[140:143], v[116:119], v[60:63]
	v_mfma_f32_16x16x32_bf16 v[56:59], v[136:139], v[116:119], v[56:59]
	v_mfma_f32_16x16x32_bf16 v[52:55], v[124:127], v[116:119], v[52:55]
	v_mfma_f32_16x16x32_bf16 v[80:83], v[136:139], v[128:131], v[80:83]
	v_mfma_f32_16x16x32_bf16 v[76:79], v[124:127], v[128:131], v[76:79]
	v_mfma_f32_16x16x32_bf16 v[72:75], v[120:123], v[128:131], v[72:75]
	v_mfma_f32_16x16x32_bf16 v[68:71], v[108:111], v[128:131], v[68:71]
	v_mfma_f32_16x16x32_bf16 v[80:83], v[144:147], v[132:135], v[80:83]
	v_mfma_f32_16x16x32_bf16 v[76:79], v[140:143], v[132:135], v[76:79]
	v_mfma_f32_16x16x32_bf16 v[72:75], v[136:139], v[132:135], v[72:75]
	v_mfma_f32_16x16x32_bf16 v[68:71], v[124:127], v[132:135], v[68:71]
	v_mfma_f32_16x16x32_bf16 v[48:51], v[136:139], v[100:103], v[48:51]
	v_mfma_f32_16x16x32_bf16 v[44:47], v[124:127], v[100:103], v[44:47]
	v_mfma_f32_16x16x32_bf16 v[40:43], v[120:123], v[100:103], v[40:43]
	v_mfma_f32_16x16x32_bf16 v[36:39], v[108:111], v[100:103], v[36:39]
	v_mfma_f32_16x16x32_bf16 v[48:51], v[144:147], v[104:107], v[48:51]
	v_mfma_f32_16x16x32_bf16 v[44:47], v[140:143], v[104:107], v[44:47]
	v_mfma_f32_16x16x32_bf16 v[40:43], v[136:139], v[104:107], v[40:43]
	v_mfma_f32_16x16x32_bf16 v[36:39], v[124:127], v[104:107], v[36:39]
	s_waitcnt lgkmcnt(0)
	v_mfma_f32_16x16x32_bf16 v[96:99], v[136:139], v[166:169], v[96:99]
	v_mfma_f32_16x16x32_bf16 v[92:95], v[124:127], v[166:169], v[92:95]
	v_mfma_f32_16x16x32_bf16 v[88:91], v[120:123], v[166:169], v[88:91]
	v_mfma_f32_16x16x32_bf16 v[84:87], v[108:111], v[166:169], v[84:87]
	v_mfma_f32_16x16x32_bf16 v[96:99], v[144:147], v[170:173], v[96:99]
	v_mfma_f32_16x16x32_bf16 v[92:95], v[140:143], v[170:173], v[92:95]
	v_mfma_f32_16x16x32_bf16 v[88:91], v[136:139], v[170:173], v[88:91]
	v_mfma_f32_16x16x32_bf16 v[84:87], v[124:127], v[170:173], v[84:87]
	s_setprio 0
	s_addk_i32 s9, 0xff80
	s_add_i32 s8, s8, -1
	s_cmpk_lg_i32 s9, 0xee80
	s_cbranch_scc1 .LBB0_835
	s_branch .LBB0_843
.Lhy_slow_835:
	s_cmp_gt_u32 s8, 31
	s_cbranch_scc1 .LBB0_839
	v_add_u32_e32 v0, s9, v154
	ds_read_b128 v[166:169], v0
	ds_read_b128 v[170:173], v0 offset:64
	s_waitcnt lgkmcnt(1)
	s_setprio 1
	v_mfma_f32_16x16x32_bf16 v[96:99], v[136:139], v[166:169], v[96:99]
	v_mfma_f32_16x16x32_bf16 v[92:95], v[124:127], v[166:169], v[92:95]
	v_mfma_f32_16x16x32_bf16 v[88:91], v[120:123], v[166:169], v[88:91]
	v_mfma_f32_16x16x32_bf16 v[84:87], v[108:111], v[166:169], v[84:87]
	s_waitcnt lgkmcnt(0)
	v_mfma_f32_16x16x32_bf16 v[96:99], v[144:147], v[170:173], v[96:99]
	v_mfma_f32_16x16x32_bf16 v[92:95], v[140:143], v[170:173], v[92:95]
	v_mfma_f32_16x16x32_bf16 v[88:91], v[136:139], v[170:173], v[88:91]
	v_mfma_f32_16x16x32_bf16 v[84:87], v[124:127], v[170:173], v[84:87]
	s_setprio 0
	s_cmp_gt_u32 s12, 31
	s_cbranch_scc0 .LBB0_840

; __device__ __forceinline__ bf16x8 hy_afrag(const bf16_t* gbase, const bool t2, const bool t1, const unsigned sh) {
;   const uint4 lo = *(const uint4*)gbase, hi = *(const uint4*)(gbase + 8);
;   const unsigned x0 = t2 ? lo.z : lo.x, x1 = t2 ? lo.w : lo.y, x2 = t2 ? hi.x : lo.z, x3 = t2 ? hi.y : lo.w,
;                  x4 = t2 ? hi.z : hi.x, x5 = t2 ? hi.w : hi.y;
;   const unsigned y0 = t1 ? x1 : x0, y1 = t1 ? x2 : x1, y2 = t1 ? x3 : x2, y3 = t1 ? x4 : x3, y4 = t1 ? x5 : x4;
;   union { unsigned u[4]; bf16x8 v; } o;
;   o.u[0] = __builtin_amdgcn_alignbit(y1, y0, sh);
;   o.u[1] = __builtin_amdgcn_alignbit(y2, y1, sh);
;   o.u[2] = __builtin_amdgcn_alignbit(y3, y2, sh);
;   o.u[3] = __builtin_amdgcn_alignbit(y4, y3, sh);
;   return o.v;
; }
; template <int LSEL>
; __device__ __forceinline__ void hy_conv(const bf16_t* Z, const bf16_t* G, f32x4 (&acc)[4][4], int w, int lane) {
;     ...
;   for (int d = i_lo - (NB - 1); d <= i_hi; ++d) {
;     bf16x8 bf[4][2];
; #pragma unroll
;     for (int k = 0; k < 4; ++k) {
;       int js = (q0 + k) * BPT - d;
;       js = min(max(js, LSEL ? -1 : 0), NB - 1);
;       const bf16_t* bp = Z + zb + 64 * js;
;       bf[k][0] = *(const bf16x8*)bp;
;       bf[k][1] = *(const bf16x8*)(bp + 32);
;     }
;     const bf16_t* gb = G + (L - 64 * d + 8 * quad - r - s);
;     bf16x8 F[6];
; #pragma unroll
;     for (int u = 0; u < 6; ++u) F[u] = hy_afrag(gb + 16 * (u - 3), t2, t1, sh);
; #pragma unroll
;     for (int k = 0; k < 4; ++k) {
;       const int js = (q0 + k) * BPT - d;
;       const bool valid = LSEL ? (js >= -1 && js <= NB - 1) : (js >= 0 && js <= NB - 1);
;       if (valid) {
; #pragma unroll
;         for (int mt = 0; mt < 4; ++mt) {
;           acc[k][mt] = __builtin_amdgcn_mfma_f32_16x16x32_bf16(F[3 - mt], bf[k][0], acc[k][mt], 0, 0, 0);
;           acc[k][mt] = __builtin_amdgcn_mfma_f32_16x16x32_bf16(F[5 - mt], bf[k][1], acc[k][mt], 0, 0, 0);
;         }
;       }
;     }
;   }
.LBB0_928:
	v_add_u32_e32 v0, s8, v176
	v_mov_b32_e32 v140, v108
	v_mov_b32_e32 v141, v109
	v_mov_b32_e32 v142, v110
	v_mov_b32_e32 v143, v111
	v_mov_b32_e32 v144, v120
	v_mov_b32_e32 v145, v121
	v_mov_b32_e32 v146, v122
	v_mov_b32_e32 v147, v123
	ds_read2_b32 v[108:109], v0 offset1:1
	ds_read2_b32 v[110:111], v0 offset0:2 offset1:3
	ds_read_b32 v2, v0 offset:16
	ds_read2_b32 v[120:121], v0 offset0:8 offset1:9
	ds_read2_b32 v[122:123], v0 offset0:10 offset1:11
	ds_read_b32 v3, v0 offset:48
	ds_read2_b32 v[124:125], v0 offset0:16 offset1:17
	ds_read2_b32 v[126:127], v0 offset0:18 offset1:19
	ds_read_b32 v177, v0 offset:80
	ds_read2_b32 v[136:137], v0 offset0:24 offset1:25
	ds_read2_b32 v[138:139], v0 offset0:26 offset1:27
	ds_read_b32 v178, v0 offset:112
	s_add_i32 s12, s9, 1
	v_med3_i32 v0, s12, 0, 31
	v_lshl_add_u32 v0, v0, 7, v153
	s_add_i32 s11, s9, 2
	ds_read_b128 v[128:131], v0
	ds_read_b128 v[132:135], v0 offset:64
	s_waitcnt lgkmcnt(11)
	v_alignbit_b32 v108, v109, v108, v152
	v_alignbit_b32 v109, v110, v109, v152
	v_alignbit_b32 v110, v111, v110, v152
	v_alignbit_b32 v111, v2, v111, v152
	v_med3_i32 v0, s11, 0, 31
	s_add_i32 s10, s9, 3
	v_lshl_add_u32 v0, v0, 7, v153
	s_min_u32 s13, s10, 31
	ds_read_b128 v[112:115], v0
	ds_read_b128 v[116:119], v0 offset:64
	s_waitcnt lgkmcnt(10)
	v_alignbit_b32 v120, v121, v120, v152
	v_alignbit_b32 v121, v122, v121, v152
	v_alignbit_b32 v122, v123, v122, v152
	v_alignbit_b32 v123, v3, v123, v152
	v_lshl_add_u32 v0, s13, 7, v153
	ds_read_b128 v[100:103], v0
	ds_read_b128 v[104:107], v0 offset:64
	s_waitcnt lgkmcnt(9)
	v_alignbit_b32 v124, v125, v124, v152
	v_alignbit_b32 v125, v126, v125, v152
	v_alignbit_b32 v126, v127, v126, v152
	v_alignbit_b32 v127, v177, v127, v152
	s_waitcnt lgkmcnt(6)
	v_alignbit_b32 v136, v137, v136, v152
	v_alignbit_b32 v137, v138, v137, v152
	v_alignbit_b32 v138, v139, v138, v152
	v_alignbit_b32 v139, v178, v139, v152
	s_waitcnt lgkmcnt(0)
	s_cmp_lt_u32 s9, 29
	s_cbranch_scc0 .Lhy_slow_928
	v_add_u32_e32 v0, s8, v154
	ds_read_b128 v[166:169], v0
	ds_read_b128 v[170:173], v0 offset:64
	s_setprio 1
	v_mfma_f32_16x16x32_bf16 v[36:39], v[136:139], v[112:115], v[36:39]
	v_mfma_f32_16x16x32_bf16 v[32:35], v[124:127], v[112:115], v[32:35]
	v_mfma_f32_16x16x32_bf16 v[28:31], v[120:123], v[112:115], v[28:31]
	v_mfma_f32_16x16x32_bf16 v[24:27], v[108:111], v[112:115], v[24:27]
	v_mfma_f32_16x16x32_bf16 v[36:39], v[144:147], v[116:119], v[36:39]
	v_mfma_f32_16x16x32_bf16 v[32:35], v[140:143], v[116:119], v[32:35]
	v_mfma_f32_16x16x32_bf16 v[28:31], v[136:139], v[116:119], v[28:31]
	v_mfma_f32_16x16x32_bf16 v[24:27], v[124:127], v[116:119], v[24:27]
	v_mfma_f32_16x16x32_bf16 v[56:59], v[136:139], v[128:131], v[56:59]
	v_mfma_f32_16x16x32_bf16 v[52:55], v[124:127], v[128:131], v[52:55]
	v_mfma_f32_16x16x32_bf16 v[48:51], v[120:123], v[128:131], v[48:51]
	v_mfma_f32_16x16x32_bf16 v[40:43], v[108:111], v[128:131], v[40:43]
	v_mfma_f32_16x16x32_bf16 v[56:59], v[144:147], v[132:135], v[56:59]
	v_mfma_f32_16x16x32_bf16 v[52:55], v[140:143], v[132:135], v[52:55]
	v_mfma_f32_16x16x32_bf16 v[48:51], v[136:139], v[132:135], v[48:51]
	v_mfma_f32_16x16x32_bf16 v[40:43], v[124:127], v[132:135], v[40:43]
	v_mfma_f32_16x16x32_bf16 v[20:23], v[136:139], v[100:103], v[20:23]
	v_mfma_f32_16x16x32_bf16 v[12:15], v[124:127], v[100:103], v[12:15]
	v_mfma_f32_16x16x32_bf16 v[8:11], v[120:123], v[100:103], v[8:11]
	v_mfma_f32_16x16x32_bf16 v[2:5], v[108:111], v[100:103], v[4:7]
	v_mfma_f32_16x16x32_bf16 v[20:23], v[144:147], v[104:107], v[20:23]
	v_mfma_f32_16x16x32_bf16 v[12:15], v[140:143], v[104:107], v[12:15]
	v_mfma_f32_16x16x32_bf16 v[8:11], v[136:139], v[104:107], v[8:11]
	v_mfma_f32_16x16x32_bf16 v[4:7], v[124:127], v[104:107], v[2:5]
	s_waitcnt lgkmcnt(0)
	v_mfma_f32_16x16x32_bf16 v[76:79], v[136:139], v[166:169], v[76:79]
	v_mfma_f32_16x16x32_bf16 v[68:71], v[124:127], v[166:169], v[68:71]
	v_mfma_f32_16x16x32_bf16 v[64:67], v[120:123], v[166:169], v[64:67]
	v_mfma_f32_16x16x32_bf16 v[60:63], v[108:111], v[166:169], v[60:63]
	v_mfma_f32_16x16x32_bf16 v[76:79], v[144:147], v[170:173], v[76:79]
	v_mfma_f32_16x16x32_bf16 v[68:71], v[140:143], v[170:173], v[68:71]
	v_mfma_f32_16x16x32_bf16 v[64:67], v[136:139], v[170:173], v[64:67]
	v_mfma_f32_16x16x32_bf16 v[60:63], v[124:127], v[170:173], v[60:63]
	s_setprio 0
	s_addk_i32 s8, 0xff80
	s_add_i32 s9, s9, -1
	s_cmpk_lg_i32 s8, 0xee80
	s_cbranch_scc1 .LBB0_928
	s_branch .LBB0_936
.Lhy_slow_928:
	s_cmp_gt_u32 s9, 31
	s_cbranch_scc1 .LBB0_932
	v_add_u32_e32 v0, s8, v154
	ds_read_b128 v[166:169], v0
	ds_read_b128 v[170:173], v0 offset:64
	s_waitcnt lgkmcnt(1)
	s_setprio 1
	v_mfma_f32_16x16x32_bf16 v[76:79], v[136:139], v[166:169], v[76:79]
	v_mfma_f32_16x16x32_bf16 v[68:71], v[124:127], v[166:169], v[68:71]
	v_mfma_f32_16x16x32_bf16 v[64:67], v[120:123], v[166:169], v[64:67]
	v_mfma_f32_16x16x32_bf16 v[60:63], v[108:111], v[166:169], v[60:63]
	s_waitcnt lgkmcnt(0)
	v_mfma_f32_16x16x32_bf16 v[76:79], v[144:147], v[170:173], v[76:79]
	v_mfma_f32_16x16x32_bf16 v[68:71], v[140:143], v[170:173], v[68:71]
	v_mfma_f32_16x16x32_bf16 v[64:67], v[136:139], v[170:173], v[64:67]
	v_mfma_f32_16x16x32_bf16 v[60:63], v[124:127], v[170:173], v[60:63]
	s_setprio 0
	s_cmp_gt_u32 s12, 31
	s_cbranch_scc0 .LBB0_933

; __device__ __forceinline__ bf16x8 hy_afrag(const bf16_t* gbase, const bool t2, const bool t1, const unsigned sh) {
;   const uint4 lo = *(const uint4*)gbase, hi = *(const uint4*)(gbase + 8);
;   const unsigned x0 = t2 ? lo.z : lo.x, x1 = t2 ? lo.w : lo.y, x2 = t2 ? hi.x : lo.z, x3 = t2 ? hi.y : lo.w,
;                  x4 = t2 ? hi.z : hi.x, x5 = t2 ? hi.w : hi.y;
;   const unsigned y0 = t1 ? x1 : x0, y1 = t1 ? x2 : x1, y2 = t1 ? x3 : x2, y3 = t1 ? x4 : x3, y4 = t1 ? x5 : x4;
;   union { unsigned u[4]; bf16x8 v; } o;
;   o.u[0] = __builtin_amdgcn_alignbit(y1, y0, sh);
;   o.u[1] = __builtin_amdgcn_alignbit(y2, y1, sh);
;   o.u[2] = __builtin_amdgcn_alignbit(y3, y2, sh);
;   o.u[3] = __builtin_amdgcn_alignbit(y4, y3, sh);
;   return o.v;
; }
; template <int LSEL>
; __device__ __forceinline__ void hy_conv(const bf16_t* Z, const bf16_t* G, f32x4 (&acc)[4][4], int w, int lane) {
;     ...
;   for (int d = i_lo - (NB - 1); d <= i_hi; ++d) {
;     bf16x8 bf[4][2];
; #pragma unroll
;     for (int k = 0; k < 4; ++k) {
;       int js = (q0 + k) * BPT - d;
;       js = min(max(js, LSEL ? -1 : 0), NB - 1);
;       const bf16_t* bp = Z + zb + 64 * js;
;       bf[k][0] = *(const bf16x8*)bp;
;       bf[k][1] = *(const bf16x8*)(bp + 32);
;     }
;     const bf16_t* gb = G + (L - 64 * d + 8 * quad - r - s);
;     bf16x8 F[6];
; #pragma unroll
;     for (int u = 0; u < 6; ++u) F[u] = hy_afrag(gb + 16 * (u - 3), t2, t1, sh);
; #pragma unroll
;     for (int k = 0; k < 4; ++k) {
;       const int js = (q0 + k) * BPT - d;
;       const bool valid = LSEL ? (js >= -1 && js <= NB - 1) : (js >= 0 && js <= NB - 1);
;       if (valid) {
; #pragma unroll
;         for (int mt = 0; mt < 4; ++mt) {
;           acc[k][mt] = __builtin_amdgcn_mfma_f32_16x16x32_bf16(F[3 - mt], bf[k][0], acc[k][mt], 0, 0, 0);
;           acc[k][mt] = __builtin_amdgcn_mfma_f32_16x16x32_bf16(F[5 - mt], bf[k][1], acc[k][mt], 0, 0, 0);
;         }
;       }
;     }
;   }
.LBB0_1112:
	v_add_u32_e32 v0, s8, v176
	v_mov_b32_e32 v138, v106
	v_mov_b32_e32 v139, v107
	v_mov_b32_e32 v140, v108
	v_mov_b32_e32 v141, v109
	v_mov_b32_e32 v142, v118
	v_mov_b32_e32 v143, v119
	v_mov_b32_e32 v144, v120
	v_mov_b32_e32 v145, v121
	ds_read2_b32 v[106:107], v0 offset1:1
	ds_read2_b32 v[108:109], v0 offset0:2 offset1:3
	ds_read_b32 v2, v0 offset:16
	ds_read2_b32 v[118:119], v0 offset0:8 offset1:9
	ds_read2_b32 v[120:121], v0 offset0:10 offset1:11
	ds_read_b32 v3, v0 offset:48
	ds_read2_b32 v[122:123], v0 offset0:16 offset1:17
	ds_read2_b32 v[124:125], v0 offset0:18 offset1:19
	ds_read_b32 v177, v0 offset:80
	ds_read2_b32 v[134:135], v0 offset0:24 offset1:25
	ds_read2_b32 v[136:137], v0 offset0:26 offset1:27
	ds_read_b32 v178, v0 offset:112
	s_add_i32 s10, s9, 1
	v_med3_i32 v0, s10, -1, 63
	v_lshl_add_u32 v0, v0, 7, v154
	s_add_i32 s10, s9, 3
	ds_read_b128 v[126:129], v0 offset:128
	ds_read_b128 v[130:133], v0 offset:192
	s_waitcnt lgkmcnt(11)
	v_alignbit_b32 v106, v107, v106, v151
	v_alignbit_b32 v107, v108, v107, v151
	v_alignbit_b32 v108, v109, v108, v151
	v_alignbit_b32 v109, v2, v109, v151
	v_med3_i32 v0, s10, -1, 63
	s_add_i32 s10, s9, 5
	v_lshl_add_u32 v0, v0, 7, v154
	s_min_i32 s10, s10, 63
	ds_read_b128 v[110:113], v0 offset:128
	ds_read_b128 v[114:117], v0 offset:192
	s_waitcnt lgkmcnt(10)
	v_alignbit_b32 v118, v119, v118, v151
	v_alignbit_b32 v119, v120, v119, v151
	v_alignbit_b32 v120, v121, v120, v151
	v_alignbit_b32 v121, v3, v121, v151
	v_lshl_add_u32 v0, s10, 7, v154
	ds_read_b128 v[98:101], v0 offset:128
	ds_read_b128 v[102:105], v0 offset:192
	s_waitcnt lgkmcnt(9)
	v_alignbit_b32 v122, v123, v122, v151
	v_alignbit_b32 v123, v124, v123, v151
	v_alignbit_b32 v124, v125, v124, v151
	v_alignbit_b32 v125, v177, v125, v151
	s_waitcnt lgkmcnt(6)
	v_alignbit_b32 v134, v135, v134, v151
	v_alignbit_b32 v135, v136, v135, v151
	v_alignbit_b32 v136, v137, v136, v151
	v_alignbit_b32 v137, v178, v137, v151
	s_waitcnt lgkmcnt(0)
	s_cmp_lt_u32 s9, 59
	s_cbranch_scc0 .Lhy_slow_1112
	v_add_u32_e32 v0, s8, v155
	ds_read_b128 v[168:171], v0
	ds_read_b128 v[172:175], v0 offset:64
	s_setprio 1
	v_mfma_f32_16x16x32_bf16 v[62:65], v[134:137], v[110:113], v[62:65]
	v_mfma_f32_16x16x32_bf16 v[58:61], v[122:125], v[110:113], v[58:61]
	v_mfma_f32_16x16x32_bf16 v[54:57], v[118:121], v[110:113], v[54:57]
	v_mfma_f32_16x16x32_bf16 v[50:53], v[106:109], v[110:113], v[50:53]
	v_mfma_f32_16x16x32_bf16 v[62:65], v[142:145], v[114:117], v[62:65]
	v_mfma_f32_16x16x32_bf16 v[58:61], v[138:141], v[114:117], v[58:61]
	v_mfma_f32_16x16x32_bf16 v[54:57], v[134:137], v[114:117], v[54:57]
	v_mfma_f32_16x16x32_bf16 v[50:53], v[122:125], v[114:117], v[50:53]
	v_mfma_f32_16x16x32_bf16 v[78:81], v[134:137], v[126:129], v[78:81]
	v_mfma_f32_16x16x32_bf16 v[74:77], v[122:125], v[126:129], v[74:77]
	v_mfma_f32_16x16x32_bf16 v[70:73], v[118:121], v[126:129], v[70:73]
	v_mfma_f32_16x16x32_bf16 v[66:69], v[106:109], v[126:129], v[66:69]
	v_mfma_f32_16x16x32_bf16 v[78:81], v[142:145], v[130:133], v[78:81]
	v_mfma_f32_16x16x32_bf16 v[74:77], v[138:141], v[130:133], v[74:77]
	v_mfma_f32_16x16x32_bf16 v[70:73], v[134:137], v[130:133], v[70:73]
	v_mfma_f32_16x16x32_bf16 v[66:69], v[122:125], v[130:133], v[66:69]
	v_mfma_f32_16x16x32_bf16 v[46:49], v[134:137], v[98:101], v[46:49]
	v_mfma_f32_16x16x32_bf16 v[42:45], v[122:125], v[98:101], v[42:45]
	v_mfma_f32_16x16x32_bf16 v[38:41], v[118:121], v[98:101], v[38:41]
	v_mfma_f32_16x16x32_bf16 v[34:37], v[106:109], v[98:101], v[34:37]
	v_mfma_f32_16x16x32_bf16 v[46:49], v[142:145], v[102:105], v[46:49]
	v_mfma_f32_16x16x32_bf16 v[42:45], v[138:141], v[102:105], v[42:45]
	v_mfma_f32_16x16x32_bf16 v[38:41], v[134:137], v[102:105], v[38:41]
	v_mfma_f32_16x16x32_bf16 v[34:37], v[122:125], v[102:105], v[34:37]
	s_waitcnt lgkmcnt(0)
	v_mfma_f32_16x16x32_bf16 v[94:97], v[134:137], v[168:171], v[94:97]
	v_mfma_f32_16x16x32_bf16 v[90:93], v[122:125], v[168:171], v[90:93]
	v_mfma_f32_16x16x32_bf16 v[86:89], v[118:121], v[168:171], v[86:89]
	v_mfma_f32_16x16x32_bf16 v[82:85], v[106:109], v[168:171], v[82:85]
	v_mfma_f32_16x16x32_bf16 v[94:97], v[142:145], v[172:175], v[94:97]
	v_mfma_f32_16x16x32_bf16 v[90:93], v[138:141], v[172:175], v[90:93]
	v_mfma_f32_16x16x32_bf16 v[86:89], v[134:137], v[172:175], v[86:89]
	v_mfma_f32_16x16x32_bf16 v[82:85], v[122:125], v[172:175], v[82:85]
	s_setprio 0
	s_add_i32 s9, s9, -1
	s_addk_i32 s8, 0xff80
	s_cmpk_lg_i32 s8, 0xdc80
	s_cbranch_scc1 .LBB0_1112
	s_branch .LBB0_1120
.Lhy_slow_1112:
	s_cmp_gt_u32 s9, 64
	s_cbranch_scc1 .LBB0_1116
	v_add_u32_e32 v0, s8, v155
	ds_read_b128 v[168:171], v0
	ds_read_b128 v[172:175], v0 offset:64
	s_waitcnt lgkmcnt(1)
	s_setprio 1
	v_mfma_f32_16x16x32_bf16 v[94:97], v[134:137], v[168:171], v[94:97]
	v_mfma_f32_16x16x32_bf16 v[90:93], v[122:125], v[168:171], v[90:93]
	v_mfma_f32_16x16x32_bf16 v[86:89], v[118:121], v[168:171], v[86:89]
	v_mfma_f32_16x16x32_bf16 v[82:85], v[106:109], v[168:171], v[82:85]
	s_waitcnt lgkmcnt(0)
	v_mfma_f32_16x16x32_bf16 v[94:97], v[142:145], v[172:175], v[94:97]
	v_mfma_f32_16x16x32_bf16 v[90:93], v[138:141], v[172:175], v[90:93]
	v_mfma_f32_16x16x32_bf16 v[86:89], v[134:137], v[172:175], v[86:89]
	v_mfma_f32_16x16x32_bf16 v[82:85], v[122:125], v[172:175], v[82:85]
	s_setprio 0
	s_add_i32 s10, s9, 2
	s_cmp_gt_u32 s10, 64
	s_cbranch_scc0 .LBB0_1117

; __device__ __forceinline__ bf16x8 hy_afrag(const bf16_t* gbase, const bool t2, const bool t1, const unsigned sh) {
;   const uint4 lo = *(const uint4*)gbase, hi = *(const uint4*)(gbase + 8);
;   const unsigned x0 = t2 ? lo.z : lo.x, x1 = t2 ? lo.w : lo.y, x2 = t2 ? hi.x : lo.z, x3 = t2 ? hi.y : lo.w,
;                  x4 = t2 ? hi.z : hi.x, x5 = t2 ? hi.w : hi.y;
;   const unsigned y0 = t1 ? x1 : x0, y1 = t1 ? x2 : x1, y2 = t1 ? x3 : x2, y3 = t1 ? x4 : x3, y4 = t1 ? x5 : x4;
;   union { unsigned u[4]; bf16x8 v; } o;
;   o.u[0] = __builtin_amdgcn_alignbit(y1, y0, sh);
;   o.u[1] = __builtin_amdgcn_alignbit(y2, y1, sh);
;   o.u[2] = __builtin_amdgcn_alignbit(y3, y2, sh);
;   o.u[3] = __builtin_amdgcn_alignbit(y4, y3, sh);
;   return o.v;
; }
; template <int LSEL>
; __device__ __forceinline__ void hy_conv(const bf16_t* Z, const bf16_t* G, f32x4 (&acc)[4][4], int w, int lane) {
;     ...
;   for (int d = i_lo - (NB - 1); d <= i_hi; ++d) {
;     bf16x8 bf[4][2];
; #pragma unroll
;     for (int k = 0; k < 4; ++k) {
;       int js = (q0 + k) * BPT - d;
;       js = min(max(js, LSEL ? -1 : 0), NB - 1);
;       const bf16_t* bp = Z + zb + 64 * js;
;       bf[k][0] = *(const bf16x8*)bp;
;       bf[k][1] = *(const bf16x8*)(bp + 32);
;     }
;     const bf16_t* gb = G + (L - 64 * d + 8 * quad - r - s);
;     bf16x8 F[6];
; #pragma unroll
;     for (int u = 0; u < 6; ++u) F[u] = hy_afrag(gb + 16 * (u - 3), t2, t1, sh);
; #pragma unroll
;     for (int k = 0; k < 4; ++k) {
;       const int js = (q0 + k) * BPT - d;
;       const bool valid = LSEL ? (js >= -1 && js <= NB - 1) : (js >= 0 && js <= NB - 1);
;       if (valid) {
; #pragma unroll
;         for (int mt = 0; mt < 4; ++mt) {
;           acc[k][mt] = __builtin_amdgcn_mfma_f32_16x16x32_bf16(F[3 - mt], bf[k][0], acc[k][mt], 0, 0, 0);
;           acc[k][mt] = __builtin_amdgcn_mfma_f32_16x16x32_bf16(F[5 - mt], bf[k][1], acc[k][mt], 0, 0, 0);
;         }
;       }
;     }
;   }
.LBB0_1205:
	v_add_u32_e32 v0, s9, v176
	v_mov_b32_e32 v138, v106
	v_mov_b32_e32 v139, v107
	v_mov_b32_e32 v140, v108
	v_mov_b32_e32 v141, v109
	v_mov_b32_e32 v142, v118
	v_mov_b32_e32 v143, v119
	v_mov_b32_e32 v144, v120
	v_mov_b32_e32 v145, v121
	ds_read2_b32 v[106:107], v0 offset1:1
	ds_read2_b32 v[108:109], v0 offset0:2 offset1:3
	ds_read_b32 v2, v0 offset:16
	ds_read2_b32 v[118:119], v0 offset0:8 offset1:9
	ds_read2_b32 v[120:121], v0 offset0:10 offset1:11
	ds_read_b32 v3, v0 offset:48
	ds_read2_b32 v[122:123], v0 offset0:16 offset1:17
	ds_read2_b32 v[124:125], v0 offset0:18 offset1:19
	ds_read_b32 v177, v0 offset:80
	ds_read2_b32 v[134:135], v0 offset0:24 offset1:25
	ds_read2_b32 v[136:137], v0 offset0:26 offset1:27
	ds_read_b32 v178, v0 offset:112
	s_add_i32 s10, s8, 1
	v_med3_i32 v0, s10, -1, 63
	v_lshl_add_u32 v0, v0, 7, v154
	s_add_i32 s10, s8, 3
	ds_read_b128 v[126:129], v0 offset:128
	ds_read_b128 v[130:133], v0 offset:192
	s_waitcnt lgkmcnt(11)
	v_alignbit_b32 v106, v107, v106, v151
	v_alignbit_b32 v107, v108, v107, v151
	v_alignbit_b32 v108, v109, v108, v151
	v_alignbit_b32 v109, v2, v109, v151
	v_med3_i32 v0, s10, -1, 63
	s_add_i32 s10, s8, 5
	v_lshl_add_u32 v0, v0, 7, v154
	s_min_i32 s10, s10, 63
	ds_read_b128 v[110:113], v0 offset:128
	ds_read_b128 v[114:117], v0 offset:192
	s_waitcnt lgkmcnt(10)
	v_alignbit_b32 v118, v119, v118, v151
	v_alignbit_b32 v119, v120, v119, v151
	v_alignbit_b32 v120, v121, v120, v151
	v_alignbit_b32 v121, v3, v121, v151
	v_lshl_add_u32 v0, s10, 7, v154
	ds_read_b128 v[98:101], v0 offset:128
	ds_read_b128 v[102:105], v0 offset:192
	s_waitcnt lgkmcnt(9)
	v_alignbit_b32 v122, v123, v122, v151
	v_alignbit_b32 v123, v124, v123, v151
	v_alignbit_b32 v124, v125, v124, v151
	v_alignbit_b32 v125, v177, v125, v151
	s_waitcnt lgkmcnt(6)
	v_alignbit_b32 v134, v135, v134, v151
	v_alignbit_b32 v135, v136, v135, v151
	v_alignbit_b32 v136, v137, v136, v151
	v_alignbit_b32 v137, v178, v137, v151
	s_waitcnt lgkmcnt(0)
	s_cmp_lt_u32 s8, 59
	s_cbranch_scc0 .Lhy_slow_1205
	v_add_u32_e32 v0, s9, v155
	ds_read_b128 v[168:171], v0
	ds_read_b128 v[172:175], v0 offset:64
	s_setprio 1
	v_mfma_f32_16x16x32_bf16 v[34:37], v[134:137], v[110:113], v[34:37]
	v_mfma_f32_16x16x32_bf16 v[30:33], v[122:125], v[110:113], v[30:33]
	v_mfma_f32_16x16x32_bf16 v[26:29], v[118:121], v[110:113], v[26:29]
	v_mfma_f32_16x16x32_bf16 v[22:25], v[106:109], v[110:113], v[22:25]
	v_mfma_f32_16x16x32_bf16 v[34:37], v[142:145], v[114:117], v[34:37]
	v_mfma_f32_16x16x32_bf16 v[30:33], v[138:141], v[114:117], v[30:33]
	v_mfma_f32_16x16x32_bf16 v[26:29], v[134:137], v[114:117], v[26:29]
	v_mfma_f32_16x16x32_bf16 v[22:25], v[122:125], v[114:117], v[22:25]
	v_mfma_f32_16x16x32_bf16 v[54:57], v[134:137], v[126:129], v[54:57]
	v_mfma_f32_16x16x32_bf16 v[50:53], v[122:125], v[126:129], v[50:53]
	v_mfma_f32_16x16x32_bf16 v[46:49], v[118:121], v[126:129], v[46:49]
	v_mfma_f32_16x16x32_bf16 v[38:41], v[106:109], v[126:129], v[38:41]
	v_mfma_f32_16x16x32_bf16 v[54:57], v[142:145], v[130:133], v[54:57]
	v_mfma_f32_16x16x32_bf16 v[50:53], v[138:141], v[130:133], v[50:53]
	v_mfma_f32_16x16x32_bf16 v[46:49], v[134:137], v[130:133], v[46:49]
	v_mfma_f32_16x16x32_bf16 v[38:41], v[122:125], v[130:133], v[38:41]
	v_mfma_f32_16x16x32_bf16 v[18:21], v[134:137], v[98:101], v[18:21]
	v_mfma_f32_16x16x32_bf16 v[14:17], v[122:125], v[98:101], v[14:17]
	v_mfma_f32_16x16x32_bf16 v[10:13], v[118:121], v[98:101], v[10:13]
	v_mfma_f32_16x16x32_bf16 v[6:9], v[106:109], v[98:101], v[6:9]
	v_mfma_f32_16x16x32_bf16 v[18:21], v[142:145], v[102:105], v[18:21]
	v_mfma_f32_16x16x32_bf16 v[14:17], v[138:141], v[102:105], v[14:17]
	v_mfma_f32_16x16x32_bf16 v[10:13], v[134:137], v[102:105], v[10:13]
	v_mfma_f32_16x16x32_bf16 v[6:9], v[122:125], v[102:105], v[6:9]
	s_waitcnt lgkmcnt(0)
	v_mfma_f32_16x16x32_bf16 v[74:77], v[134:137], v[168:171], v[74:77]
	v_mfma_f32_16x16x32_bf16 v[66:69], v[122:125], v[168:171], v[66:69]
	v_mfma_f32_16x16x32_bf16 v[62:65], v[118:121], v[168:171], v[62:65]
	v_mfma_f32_16x16x32_bf16 v[58:61], v[106:109], v[168:171], v[58:61]
	v_mfma_f32_16x16x32_bf16 v[74:77], v[142:145], v[172:175], v[74:77]
	v_mfma_f32_16x16x32_bf16 v[66:69], v[138:141], v[172:175], v[66:69]
	v_mfma_f32_16x16x32_bf16 v[62:65], v[134:137], v[172:175], v[62:65]
	v_mfma_f32_16x16x32_bf16 v[58:61], v[122:125], v[172:175], v[58:61]
	s_setprio 0
	s_add_i32 s8, s8, -1
	s_addk_i32 s9, 0xff80
	s_cmpk_lg_i32 s9, 0xdc80
	s_cbranch_scc1 .LBB0_1205
	s_branch .LBB0_1213
.Lhy_slow_1205:
	s_cmp_gt_u32 s8, 64
	s_cbranch_scc1 .LBB0_1209
	v_add_u32_e32 v0, s9, v155
	ds_read_b128 v[168:171], v0
	ds_read_b128 v[172:175], v0 offset:64
	s_waitcnt lgkmcnt(1)
	s_setprio 1
	v_mfma_f32_16x16x32_bf16 v[74:77], v[134:137], v[168:171], v[74:77]
	v_mfma_f32_16x16x32_bf16 v[66:69], v[122:125], v[168:171], v[66:69]
	v_mfma_f32_16x16x32_bf16 v[62:65], v[118:121], v[168:171], v[62:65]
	v_mfma_f32_16x16x32_bf16 v[58:61], v[106:109], v[168:171], v[58:61]
	s_waitcnt lgkmcnt(0)
	v_mfma_f32_16x16x32_bf16 v[74:77], v[142:145], v[172:175], v[74:77]
	v_mfma_f32_16x16x32_bf16 v[66:69], v[138:141], v[172:175], v[66:69]
	v_mfma_f32_16x16x32_bf16 v[62:65], v[134:137], v[172:175], v[62:65]
	v_mfma_f32_16x16x32_bf16 v[58:61], v[122:125], v[172:175], v[58:61]
	s_setprio 0
	s_add_i32 s10, s8, 2
	s_cmp_gt_u32 s10, 64
	s_cbranch_scc0 .LBB0_1210
